# attention job queue split into 8 per-XCD sub-queues with stealing (jobs sharing K/V run on one XCD)
# speedup vs baseline: 1.0098x; 1.0018x over previous
; DI void diff_job8(const Params& p, int layer, int b, int head, int qb, unsigned char* smem) {
;     ...
;   const float lam_init = 0.8f - 0.6f * expf(-0.3f * (float)layer);
;   {
;     float a = p.lq1[layer * 64 + lane] * p.lk1[layer * 64 + lane];
;     float c = p.lq2[layer * 64 + lane] * p.lk2[layer * 64 + lane];
; DI void phase_attn(const Params& p, int layer, int phase, unsigned char* smem) {
;   u32* ctr = p.ctr + phase;
;   for (;;) {
.LBB0_355:
	s_and_b64 vcc, exec, s[2:3]
	s_cbranch_vccz .LBB0_949
	v_readlane_b32 s6, v252, 28
	v_readlane_b32 s2, v252, 26
	s_mov_b32 s4, s2
	v_cvt_f32_i32_e32 v0, s6
	s_ashr_i32 s5, s2, 31
	s_mov_b32 s2, 0x3fb8aa3b
	v_readlane_b32 s3, v252, 27
	v_mul_f32_e32 v0, 0xbe99999a, v0
	s_waitcnt lgkmcnt(0)
	v_mul_f32_e32 v2, 0x3fb8aa3b, v0
	v_fma_f32 v3, v0, s2, -v2
	s_mov_b32 s2, s4
	v_rndne_f32_e32 v4, v2
	v_writelane_b32 v252, s2, 26
	v_fmac_f32_e32 v3, 0x32a5705f, v0
	v_sub_f32_e32 v2, v2, v4
	v_writelane_b32 v252, s3, 27
	s_and_b32 s4, s4, 8
	s_add_i32 s4, s4, 16
	s_getreg_b32 s2, hwreg(HW_REG_XCC_ID, 0, 4)
	s_and_b32 s2, s2, 7
	s_mov_b32 s3, 0
	s_nop 0
	v_writelane_b32 v252, s2, 62
	v_writelane_b32 v252, s3, 61
	s_lshl_b64 s[2:3], s[4:5], 2
	s_load_dwordx2 s[4:5], s[0:1], 0x178
	v_add_f32_e32 v2, v2, v3
	v_exp_f32_e32 v2, v2
	v_cvt_i32_f32_e32 v3, v4
	s_load_dwordx16 s[56:71], s[0:1], 0x40
	s_waitcnt lgkmcnt(0)
	s_add_u32 s52, s4, s2
	s_mov_b32 s2, 0xc2ce8ed0
	v_ldexp_f32 v2, v2, v3
	v_cmp_ngt_f32_e32 vcc, s2, v0
	s_mov_b32 s2, 0x42b17218
	s_addc_u32 s53, s5, s3
	v_cndmask_b32_e32 v2, 0, v2, vcc
	v_cmp_nlt_f32_e32 vcc, s2, v0
	s_lshl_b32 s2, s6, 7
	s_ashr_i32 s3, s2, 31
	v_cndmask_b32_e32 v0, v211, v2, vcc
	s_lshl_b32 s30, s6, 6
	s_lshl_b64 s[2:3], s[2:3], 2
	v_fmamk_f32 v146, v0, 0xbf19999a, v201
	s_add_u32 s54, s68, s2
	v_sub_f32_e32 v147, 1.0, v146
	s_addc_u32 s55, s69, s3
	s_branch .LBB0_360

; DI int next_job(u32* ctr, unsigned char* smem) {
;   int* sj = (int*)(smem + SJOB_OFF);
;   __syncthreads();
;   if (threadIdx.x == 0) *sj = (int)atomicAdd(ctr, 1u);
;   __syncthreads();
;   return *sj;
; }
.LBB0_360:
	s_barrier
	s_mov_b64 s[2:3], exec
	v_readlane_b32 s4, v253, 1
	v_readlane_b32 s5, v253, 2
	s_and_b64 s[4:5], s[2:3], s[4:5]
	s_mov_b64 exec, s[4:5]
	s_cbranch_execz .LBB0_364
	v_readlane_b32 s6, v252, 62
	v_readlane_b32 s7, v252, 61
	s_nop 0
.Lxq_loop:
	s_cmp_lt_u32 s7, 8
	s_cbranch_scc0 .Lxq_done
	s_lshl_b32 s4, s6, 2
	s_add_u32 s4, s52, s4
	s_addc_u32 s5, s53, 0
	v_mov_b32_e32 v2, 1
	global_atomic_add v2, v1, v2, s[4:5] sc0
	s_waitcnt vmcnt(0)
	v_readfirstlane_b32 s10, v2
	s_nop 0
	s_cmpk_lt_u32 s10, 0x14a
	s_cbranch_scc1 .Lxq_got
	s_add_i32 s6, s6, 1
	s_and_b32 s6, s6, 7
	s_add_i32 s7, s7, 1
	s_branch .Lxq_loop
.Lxq_got:
	s_cmpk_lt_u32 s10, 0x84
	s_cbranch_scc0 .Lxq_hi
	s_lshr_b32 s4, s10, 2
	s_lshl_b32 s4, s4, 5
	s_and_b32 s5, s10, 3
	s_lshl_b32 s5, s5, 3
	s_add_i32 s4, s4, s5
	s_add_i32 s10, s4, s6
	s_branch .Lxq_wr
.Lxq_hi:
	s_sub_i32 s4, s10, 0x84
	s_lshl_b32 s4, s4, 3
	s_add_i32 s4, s4, s6
	s_add_i32 s10, s4, 0x420
	s_branch .Lxq_wr
.Lxq_done:
	s_movk_i32 s10, 0xa50
.Lxq_wr:
	v_writelane_b32 v252, s6, 62
	v_writelane_b32 v252, s7, 61
	v_mov_b32_e32 v0, s10
	ds_write_b32 v200, v0
